# attention phase: waves 0-3 (comp 0) run at s_setprio 2 so the two waves sharing a SIMD de-phase (one in MFMA while the other in softmax VALU); reset to 0 at phase end
# baseline (speedup 1.0000x reference)
.LBB0_1090:
	v_readlane_b32 s4, v254, 62
	v_readlane_b32 s5, v254, 63
	s_and_b64 vcc, exec, s[4:5]
	s_barrier
	s_cbranch_vccnz .LBB0_1124
	v_readfirstlane_b32 s4, v179
	s_cmpk_lt_u32 s4, 0x100
	s_cbranch_scc0 .Lprio_skip
	s_setprio 2

.LBB0_1124:
	s_setprio 0
	s_mov_b64 s[6:7], s[26:27]
	s_getreg_b32 s8, hwreg(HW_REG_XCC_ID, 0, 4)
	s_waitcnt vmcnt(0)
	s_barrier
	s_mov_b64 s[4:5], exec
	v_readlane_b32 s10, v254, 0
	v_readlane_b32 s11, v254, 1
	v_readlane_b32 s40, v254, 34
	s_and_b64 s[10:11], s[4:5], s[10:11]
	v_readlane_b32 s41, v254, 35
	s_mov_b64 exec, s[10:11]
	s_cbranch_execz .LBB0_1177
	v_readlane_b32 s9, v254, 36
	s_waitcnt vmcnt(0) expcnt(0) lgkmcnt(0)
	s_and_b32 s18, s8, 15
	v_mov_b32_e32 v1, s9
	ds_read_b32 v3, v1
	v_readlane_b32 s9, v254, 37
	s_waitcnt lgkmcnt(0)
	v_cmp_ne_u32_e32 vcc, 0, v3
	v_mov_b32_e32 v1, s9
	ds_read_b32 v2, v1
	s_cbranch_vccnz .LBB0_1141
	s_add_u32 s8, s6, 0x10200
	s_addc_u32 s9, s7, 0
	s_add_u32 s10, s6, 0x10400
	s_addc_u32 s11, s7, 0
	s_add_u32 s12, s6, 0x10500
	s_addc_u32 s13, s7, 0
	s_add_u32 s14, s6, 0x10600
	s_addc_u32 s15, s7, 0
	s_add_u32 s16, s6, 0x10700
	s_addc_u32 s17, s7, 0
	s_add_u32 s20, s6, 0x10800
	s_addc_u32 s21, s7, 0
	s_add_u32 s22, s6, 0x10900
	s_addc_u32 s23, s7, 0
	s_add_u32 s28, s6, 0x10a00
	s_addc_u32 s29, s7, 0
	s_add_u32 s34, s6, 0x10b00
	s_addc_u32 s35, s7, 0
	s_add_u32 s38, s6, 0x10c00
	s_addc_u32 s39, s7, 0
	s_add_u32 s40, s6, 0x10d00
	s_addc_u32 s41, s7, 0
	s_add_u32 s42, s6, 0x10e00
	s_addc_u32 s43, s7, 0
	s_add_u32 s48, s6, 0x10f00
	s_addc_u32 s49, s7, 0
	s_add_u32 s50, s6, 0x11000
	s_addc_u32 s51, s7, 0
	s_add_u32 s52, s6, 0x11100
	s_addc_u32 s53, s7, 0
	s_add_u32 s56, s6, 0x11200
	s_addc_u32 s57, s7, 0
	s_add_u32 s58, s6, 0x11300
	s_addc_u32 s59, s7, 0
	s_mov_b32 s19, 1
	s_branch .LBB0_1129
